# one static s_setprio 1 for waves 4-7 during the attention phase (reset at phase exit)
# baseline (speedup 1.0000x reference)
; #define LAS __attribute__((address_space(3)))
; DI void attn_unit(LAS unsigned char* lds, const Args& a, int bg, int qt) {
;     const int tid = threadIdx.x, lane = tid & 63, w = __builtin_amdgcn_readfirstlane(tid >> 6);
;     const int hl = w >> 1, qs = w & 1, ql = lane & 31, hi = lane >> 5, qloc = 32 * qs + ql;
;     const int b = bg >> 1, g = bg & 1, head = g * 4 + hl;
;     const size_t tok = (size_t)b * SEQ + qt * 64 + qloc;
;     const bf16_t* Qb = (const bf16_t*)(a.ws + WS_Q); const bf16_t* KVb = (const bf16_t*)(a.ws + WS_KV);
;     const float* NG = (const float*)(a.ws + WS_NG); bf16_t* AO = (bf16_t*)(a.ws + WS_AO);
;     bf16x8 qf[4];
;     { const bf16_t* qp = Qb + tok * 512 + head * 64 + hi * 8;
; #pragma unroll
;       for (int d0 = 0; d0 < 4; ++d0) qf[d0] = *(const bf16x8*)(qp + 16 * d0); }
;     LAS float* GT = (LAS float*)(lds + LDS_GATE) + tid;
;     GT[0] = NG[tok * 24 + head]; GT[512] = NG[tok * 24 + 8 + head]; GT[1024] = NG[tok * 24 + 16 + head];
;     LAS float* IMP = (LAS float*)(lds + LDS_IMP); LAS float* VAL = (LAS float*)(lds + LDS_VAL);
;     LAS unsigned* MSK = (LAS unsigned*)(lds + LDS_MSK); LAS int* LIST = (LAS int*)(lds + LDS_LIST);
;     const unsigned lds_base = (unsigned)(uintptr_t)lds;
;     const size_t kofs = (size_t)lane * 64 + w * 8;
;     const size_t vofs = (size_t)(16 * (w & 3) + (lane >> 2)) * 64 + 32 * (w >> 2) + 8 * (lane & 3);
;     ...
;     const bf16_t* KC = (const bf16_t*)(a.ws + WS_KCC) + (size_t)bg * 8192;
;     const bf16_t* KS = KVb + 2 * KV_SLOT + (size_t)bg * SEQ * 64;
;     constexpr size_t VC_OFF = (WS_VCC - WS_KCC) / 2;
;     f32x16 oacc[2], o[2], sp[2];
; #pragma unroll
;     for (int r = 0; r < 16; ++r) { oacc[0][r] = 0.f; oacc[1][r] = 0.f; o[0][r] = 0.f; o[1][r] = 0.f; }
;     float m_ref = 0.f, l_run = 0.f;
;     const int pos = qt * 64 + qloc;
;     float mu0 = 0.f, xcross = 0.f;
;     LAS float* ip = IMP + (hl * 64 + qloc) * IMP_PITCH;
; __global__ void __launch_bounds__(512, 2) mk_fwd(Args args) {
;     ...
;     if (IN(6)) {
;         for (int uix = vcu; uix < 2048; uix += G) {
;             const int v = uix & 255, i = uix >> 8, x = v >> 5, k = v & 31, bg = x * 8 + i;
;             const int f = (k + 8 * (i >> 1)) & 31, qt = (i & 1) ? 31 - f : f;
.LBB0_735:
	s_cmp_lt_i32 s26, 7
	s_cselect_b64 s[6:7], -1, 0
	s_and_b64 s[34:35], s[6:7], s[4:5]
	s_cmpk_lt_i32 s74, 0x800
	s_cselect_b64 s[4:5], -1, 0
	s_and_b64 s[4:5], s[34:35], s[4:5]
	s_andn2_b64 vcc, exec, s[4:5]
	s_cbranch_vccnz .LBB0_884
	s_load_dwordx2 s[8:9], s[0:1], 0xc0
	v_lshlrev_b32_e32 v4, 1, v184
	v_and_b32_e32 v98, 31, v184
	v_lshrrev_b32_e32 v2, 5, v146
	s_waitcnt lgkmcnt(0)
	v_lshlrev_b32_e32 v3, 3, v184
	s_add_u32 s36, s8, 0xc000000
	s_addc_u32 s37, s9, 0
	s_add_u32 s38, s8, 0x2e200000
	s_addc_u32 s39, s9, 0
	s_add_i32 s4, 0, 0x1ac00
	s_add_u32 s56, s8, 0x33000000
	s_addc_u32 s57, s9, 0
	s_add_u32 s58, s8, 0x12000000
	v_and_b32_e32 v189, 32, v4
	v_lshlrev_b32_e32 v102, 3, v2
	v_lshl_add_u32 v133, v184, 2, s4
	v_and_b32_e32 v185, 24, v3
	s_addc_u32 s59, s9, 0
	s_add_i32 s4, 0, 0x10000
	v_lshlrev_b32_e32 v1, 2, v2
	v_lshlrev_b32_e32 v187, 10, v2
	v_lshlrev_b32_e32 v190, 8, v2
	v_add_u32_e32 v2, 0, v189
	v_lshlrev_b32_e32 v4, 2, v98
	s_add_i32 s10, 0, 0x18400
	v_add3_u32 v7, v2, v185, v190
	v_lshrrev_b32_e32 v2, 5, v184
	v_add_u32_e32 v9, s4, v4
	v_add_u32_e32 v4, s10, v4
	s_add_i32 s10, 0, 0x1c400
	s_waitcnt vmcnt(0)
	v_mad_u32_u24 v192, v2, 12, s10
	v_lshrrev_b32_e32 v6, 2, v184
	v_and_b32_e32 v6, 4, v6
	v_add_u32_e32 v194, 0x300, v192
	v_add_u32_e32 v196, 0x600, v192
	v_add_u32_e32 v198, 0x900, v192
	v_add_u32_e32 v8, 16, v2
	v_add_u32_e32 v200, 0xc0, v192
	v_add_u32_e32 v202, 0x3c0, v192
	v_add_u32_e32 v204, 0x6c0, v192
	v_add_u32_e32 v206, 0x9c0, v192
	v_or_b32_e32 v13, 32, v2
	v_add_u32_e32 v208, 0x180, v192
	v_add_u32_e32 v210, 0x480, v192
	v_add_u32_e32 v212, 0x780, v192
	v_add_u32_e32 v214, 0xa80, v192
	v_add_u32_e32 v15, 48, v2
	v_add_u32_e32 v216, 0x240, v192
	v_add_u32_e32 v218, 0x540, v192
	v_add_u32_e32 v220, 0x840, v192
	v_add_u32_e32 v222, 0xb40, v192
	v_add_u32_e32 v193, v192, v6
	v_add_u32_e32 v195, v194, v6
	v_add_u32_e32 v197, v196, v6
	v_add_u32_e32 v199, v198, v6
	v_lshlrev_b32_e32 v12, 7, v2
	v_add_u32_e32 v201, v200, v6
	v_add_u32_e32 v203, v202, v6
	v_add_u32_e32 v205, v204, v6
	v_add_u32_e32 v207, v206, v6
	v_lshlrev_b32_e32 v10, 7, v8
	v_add_u32_e32 v209, v208, v6
	v_add_u32_e32 v211, v210, v6
	v_add_u32_e32 v213, v212, v6
	v_add_u32_e32 v215, v214, v6
	v_lshlrev_b32_e32 v14, 7, v13
	v_add_u32_e32 v217, v216, v6
	v_add_u32_e32 v219, v218, v6
	v_add_u32_e32 v221, v220, v6
	v_add_u32_e32 v223, v222, v6
	v_lshlrev_b32_e32 v6, 7, v15
	v_add_u32_e32 v224, v4, v12
	s_add_i32 s10, 0, 0x1a400
	v_add_u32_e32 v226, v4, v10
	v_add_u32_e32 v228, v4, v14
	v_add_u32_e32 v230, v4, v6
	v_lshrrev_b32_e32 v4, 3, v146
	v_lshlrev_b32_e32 v188, 4, v98
	v_mul_u32_u24_e32 v11, 0x84, v2
	v_lshl_add_u32 v225, v2, 2, s10
	v_and_b32_e32 v2, 56, v3
	v_mul_u32_u24_e32 v233, 0x90, v4
	v_lshlrev_b32_e32 v4, 9, v4
	v_and_b32_e32 v191, 0xc0, v188
	v_add_u32_e32 v5, 0, v187
	v_lshl_add_u32 v227, v8, 2, s10
	s_add_u32 s61, s8, 0x2e800000
	v_or_b32_e32 v6, 0x1000, v4
	v_or_b32_e32 v8, 0x2000, v4
	v_or_b32_e32 v10, 0x3000, v4
	v_lshlrev_b32_e32 v138, 1, v2
	v_mbcnt_lo_u32_b32 v2, -1, 0
	v_mov_b32_e32 v101, 0
	s_mov_b32 s41, 0
	v_lshlrev_b32_e32 v135, 6, v146
	v_lshrrev_b32_e32 v147, 2, v146
	v_add_u32_e32 v186, s4, v1
	v_or_b32_e32 v99, 3, v1
	v_or_b32_e32 v104, 2, v1
	v_or_b32_e32 v103, 9, v1
	v_or_b32_e32 v106, 8, v1
	v_or_b32_e32 v105, 11, v1
	v_or_b32_e32 v108, 10, v1
	v_or_b32_e32 v107, 17, v1
	v_or_b32_e32 v110, 16, v1
	v_or_b32_e32 v109, 19, v1
	v_or_b32_e32 v112, 18, v1
	v_or_b32_e32 v111, 25, v1
	v_or_b32_e32 v114, 24, v1
	v_or_b32_e32 v113, 27, v1
	v_or_b32_e32 v116, 26, v1
	v_or_b32_e32 v115, 33, v1
	v_or_b32_e32 v118, 32, v1
	v_or_b32_e32 v117, 35, v1
	v_or_b32_e32 v120, 34, v1
	v_or_b32_e32 v119, 41, v1
	v_or_b32_e32 v122, 40, v1
	v_or_b32_e32 v121, 43, v1
	v_or_b32_e32 v124, 42, v1
	v_or_b32_e32 v123, 49, v1
	v_or_b32_e32 v126, 48, v1
	v_or_b32_e32 v125, 51, v1
	v_or_b32_e32 v128, 50, v1
	v_or_b32_e32 v127, 57, v1
	v_or_b32_e32 v130, 56, v1
	v_or_b32_e32 v129, 59, v1
	v_or_b32_e32 v132, 58, v1
	v_cmp_gt_u32_e64 s[42:43], 32, v146
	v_cmp_eq_u32_e64 s[4:5], 16, v98
	v_cmp_eq_u32_e64 s[6:7], 0, v98
	s_movk_i32 s60, 0x84
	v_and_b32_e32 v134, 32, v184
	v_lshl_add_u32 v229, v13, 2, s10
	v_lshl_add_u32 v231, v15, 2, s10
	s_addc_u32 s62, s9, 0
	v_mul_u32_u24_e32 v232, 0x90, v98
	v_mov_b32_e32 v131, v98
	v_add_u32_e32 v234, 0, v12
	v_lshlrev_b32_e32 v136, 1, v102
	s_movk_i32 s63, 0x60
	s_mov_b64 s[44:45], 0x100000
	s_mov_b64 s[46:47], 0x2000
	s_mov_b64 s[48:49], 0x102000
	s_mov_b64 s[50:51], 0x1000000
	s_mov_b32 s64, 0xff800000
	s_mov_b32 s65, 0x41800000
	s_mov_b32 s66, 0xc1800000
	s_movk_i32 s67, 0xff80
	s_add_i32 s68, 0, 0x1a900
	s_add_i32 s69, 0, 0x1a804
	s_add_i32 s70, 0, 0x1a808
	s_add_i32 s71, 0, 0x1a80c
	v_lshlrev_b32_e32 v140, 1, v4
	v_lshlrev_b32_e32 v142, 1, v6
	v_lshlrev_b32_e32 v144, 1, v8
	v_lshlrev_b32_e32 v148, 1, v10
	v_mov_b32_e32 v235, 0x60
	v_add_u32_e32 v236, v5, v188
	v_mov_b32_e32 v237, 0xff800000
	v_add_u32_e32 v238, v7, v191
	v_mbcnt_hi_u32_b32 v239, -1, v2
	v_add_u32_e32 v240, v9, v11
	v_mov_b32_e32 v241, 0x461c4000
	v_readfirstlane_b32 s82, v184
	s_nop 3
	s_cmp_ge_u32 s82, 0x100
	s_cbranch_scc0 .Lprio_skip
	s_setprio 1
.Lprio_skip:
	s_branch .LBB0_739

; DI unsigned xb_ld(unsigned* p)              { return __hip_atomic_load(p, __ATOMIC_RELAXED, __HIP_MEMORY_SCOPE_AGENT); }
; DI void xcd_barrier_complete(unsigned* bar, unsigned x, unsigned& nloc, unsigned& nx) {
;     const unsigned G = gridDim.x * gridDim.y * gridDim.z;
;     unsigned sum, cnt, mine, sp = 0u;
;     for (;;) {
;         sum = 0u; cnt = 0u; mine = 0u;
; #pragma unroll
;         for (unsigned j = 0; j < 16; ++j) { const unsigned c = xb_ld(&bar[XB_XCNT(j)]); sum += c; cnt += (c > 0u) ? 1u : 0u; mine = (j == x) ? c : mine; }
;         if (sum == G) break;
; DI void xcd_barrier(const XcdBarrier& b) {
;     asm volatile("s_waitcnt vmcnt(0)" ::: "memory");
;     __syncthreads();
;     if (threadIdx.x == 0) {
;         unsigned* bar = b.bar;
;         __builtin_amdgcn_s_waitcnt(0);
;         unsigned nloc = b.st[0], nx = b.st[1];
;         if (nloc == 0u) { xcd_barrier_complete(bar, b.x, nloc, nx); b.st[0] = nloc; b.st[1] = nx; }
.LBB0_884:
	s_setprio 0
	s_nop 0
	s_cmp_gt_i32 s27, 7
	s_cselect_b64 s[4:5], -1, 0
	s_and_b64 s[6:7], s[34:35], s[4:5]
	s_andn2_b64 vcc, exec, s[6:7]
	s_cbranch_vccnz .LBB0_952
	s_cmp_gt_i32 s26, -1
	s_mov_b64 s[6:7], -1
	s_cbranch_scc0 .LBB0_939
	s_waitcnt vmcnt(0)
	s_waitcnt vmcnt(0) lgkmcnt(0)
	s_barrier
	s_and_saveexec_b64 s[6:7], s[14:15]
	s_cbranch_execz .LBB0_938
	s_add_i32 s8, 0, 0x23fc0
	v_mov_b32_e32 v1, s8
	s_waitcnt vmcnt(0) expcnt(0) lgkmcnt(0)
	ds_read_b32 v3, v1
	s_add_i32 s8, 0, 0x23fc4
	v_mov_b32_e32 v1, s8
	ds_read_b32 v1, v1
	s_waitcnt lgkmcnt(1)
	v_cmp_ne_u32_e32 vcc, 0, v3
	s_cbranch_vccnz .LBB0_902
	s_add_u32 s8, s24, 0x1000
	s_addc_u32 s9, s25, 0
	s_add_u32 s10, s24, 0x1100
	s_addc_u32 s11, s25, 0
	s_add_u32 s12, s24, 0x1200
	s_addc_u32 s13, s25, 0
	s_mul_i32 s28, s87, s3
	s_add_u32 s16, s24, 0x1300
	s_mul_i32 s28, s28, s86
	s_addc_u32 s17, s25, 0
	s_mov_b32 s29, 1
	v_mov_b32_e32 v17, 0
	s_branch .LBB0_890
